# RG-LRU d=1 direction: chunk-summary block moved from wave 0 (which has the 7-step carry chain there) to wave 7 (no chain) to balance the per-sub-block critical path
# speedup vs baseline: 1.0076x; 1.0009x over previous
.LBB0_270:
	v_cndmask_b32_e64 v0, 1.0, v35, s[4:5]
	v_cndmask_b32_e64 v35, 0, v37, s[4:5]
	v_fmac_f32_e32 v35, v0, v1
	v_mul_f32_e32 v0, v0, v8
	v_cndmask_b32_e64 v37, v38, v41, s[4:5]
	v_cndmask_b32_e64 v36, v36, v40, s[4:5]
	v_fmac_f32_e32 v36, v37, v1
	v_mul_f32_e32 v37, v37, v8
	v_cndmask_b32_e64 v40, v46, v88, s[4:5]
	v_cndmask_b32_e64 v41, v43, v47, s[4:5]
	v_fmac_f32_e32 v41, v40, v1
	v_mul_f32_e32 v40, v40, v8
	s_ashr_i32 s13, s12, 31
	v_lshlrev_b32_e32 v88, 2, v93
	v_fmac_f32_e32 v25, v32, v41
	v_mul_f32_e32 v32, v32, v40
	v_fmac_f32_e32 v9, v34, v36
	v_mul_f32_e32 v34, v34, v37
	v_fmac_f32_e32 v10, v31, v36
	v_mul_f32_e32 v31, v31, v37
	v_fmac_f32_e32 v5, v28, v36
	v_mul_f32_e32 v28, v28, v37
	v_fmac_f32_e32 v11, v18, v36
	v_mul_f32_e32 v18, v18, v37
	v_fmac_f32_e32 v6, v12, v35
	v_mul_f32_e32 v36, v0, v12
	v_fmac_f32_e32 v4, v13, v35
	v_mul_f32_e32 v37, v0, v13
	s_lshl_b64 s[6:7], s[12:13], 12
	s_add_u32 s100, s24, s6
	s_addc_u32 s101, s25, s7
	v_fmac_f32_e32 v23, v29, v41
	v_mul_f32_e32 v29, v29, v40
	v_fmac_f32_e32 v21, v26, v41
	v_mul_f32_e32 v26, v26, v40
	v_fmac_f32_e32 v3, v16, v41
	v_mul_f32_e32 v40, v16, v40
	v_lshlrev_b32_e32 v12, 14, v92
	v_or_b32_e32 v12, v12, v88
	v_cvt_pk_bf16_f32 v16, v25, v32
	v_mov_b32_e32 v13, v89
	v_cndmask_b32_e64 v38, v42, v45, s[4:5]
	v_cndmask_b32_e64 v39, v39, v44, s[4:5]
	v_fmac_f32_e32 v39, v38, v1
	v_mul_f32_e32 v38, v38, v8
	v_mov_b32_e32 v96, v12
	v_or_b32_e32 v88, 0x1000, v12
	v_fmac_f32_e32 v22, v33, v39
	v_mul_f32_e32 v33, v33, v38
	v_fmac_f32_e32 v20, v30, v39
	v_mul_f32_e32 v30, v30, v38
	v_fmac_f32_e32 v19, v27, v39
	v_mul_f32_e32 v27, v27, v38
	v_fmac_f32_e32 v7, v17, v39
	v_mul_f32_e32 v38, v17, v38
	v_lshl_or_b32 v175, v138, 2, v133
	global_load_dword v172, v175, s[42:43]
	global_load_dword v173, v175, s[36:37]
	global_load_dword v174, v175, s[40:41]
	global_store_dword v96, v16, s[100:101] nt
	v_cvt_pk_bf16_f32 v13, v23, v29
	global_store_dword v88, v13, s[100:101] nt
	v_or_b32_e32 v98, 0x2000, v12
	v_mov_b32_e32 v99, v89
	v_cvt_pk_bf16_f32 v13, v21, v26
	v_or_b32_e32 v100, 0x3000, v12
	v_mov_b32_e32 v101, v89
	global_store_dword v98, v13, s[100:101] nt
	v_cvt_pk_bf16_f32 v3, v3, v40
	global_store_dword v100, v3, s[100:101] nt
	v_or_b32_e32 v102, 0x8000, v12
	v_mov_b32_e32 v103, v89
	v_cvt_pk_bf16_f32 v3, v22, v33
	global_store_dword v102, v3, s[100:101] nt
	v_or_b32_e32 v104, 0x9000, v12
	v_mov_b32_e32 v105, v89
	v_cvt_pk_bf16_f32 v3, v20, v30
	global_store_dword v104, v3, s[100:101] nt
	v_or_b32_e32 v106, 0xa000, v12
	v_mov_b32_e32 v107, v89
	v_cvt_pk_bf16_f32 v3, v19, v27
	global_store_dword v106, v3, s[100:101] nt
	v_or_b32_e32 v108, 0xb000, v12
	v_mov_b32_e32 v109, v89
	v_cvt_pk_bf16_f32 v3, v7, v38
	global_store_dword v108, v3, s[100:101] nt
	v_or_b32_e32 v110, 0x10000, v12
	v_mov_b32_e32 v111, v89
	v_cvt_pk_bf16_f32 v3, v9, v34
	global_store_dword v110, v3, s[100:101] nt
	v_or_b32_e32 v112, 0x11000, v12
	v_mov_b32_e32 v113, v89
	v_cvt_pk_bf16_f32 v3, v10, v31
	global_store_dword v112, v3, s[100:101] nt
	v_or_b32_e32 v114, 0x12000, v12
	v_mov_b32_e32 v115, v89
	v_cvt_pk_bf16_f32 v3, v5, v28
	global_store_dword v114, v3, s[100:101] nt
	v_or_b32_e32 v116, 0x13000, v12
	v_mov_b32_e32 v117, v89
	v_cvt_pk_bf16_f32 v3, v11, v18
	global_store_dword v116, v3, s[100:101] nt
	v_or_b32_e32 v118, 0x18000, v12
	v_mov_b32_e32 v119, v89
	v_cvt_pk_bf16_f32 v3, v6, v36
	global_store_dword v118, v3, s[100:101] nt
	v_or_b32_e32 v120, 0x19000, v12
	v_mov_b32_e32 v121, v89
	v_fmac_f32_e32 v2, v14, v35
	v_mul_f32_e32 v14, v0, v14
	v_cvt_pk_bf16_f32 v3, v4, v37
	v_fmac_f32_e32 v15, v24, v35
	v_mul_f32_e32 v0, v0, v24
	s_lshl_b32 s8, s65, 11
	global_store_dword v120, v3, s[100:101] nt
	v_or_b32_e32 v122, 0x1a000, v12
	v_mov_b32_e32 v123, v89
	s_or_b32 s8, s8, s76
	v_cvt_pk_bf16_f32 v4, v2, v14
	v_or_b32_e32 v124, 0x1b000, v12
	v_mov_b32_e32 v125, v89
	v_add_u32_e32 v97, 0xfffffe40, v90
	v_cmp_gt_u32_e64 s[6:7], 32, v97
	v_add_u32_e32 v92, s8, v97
	global_store_dword v122, v4, s[100:101] nt
	v_cvt_pk_bf16_f32 v2, v15, v0
	v_lshl_add_u32 v90, v97, 3, 16
	global_store_dword v124, v2, s[100:101] nt
	s_and_saveexec_b64 s[8:9], s[6:7]
	s_cbranch_execz .LBB0_272
	ds_read2_b64 v[0:3], v90 offset0:192 offset1:224
	ds_read2_b64 v[4:7], v90 offset0:128 offset1:160
	ds_read2_b64 v[8:11], v90 offset0:64 offset1:96
	ds_read2_b64 v[12:15], v90 offset1:32
	v_ashrrev_i32_e32 v93, 31, v92
	s_waitcnt lgkmcnt(3)
	v_fma_f32 v16, 0, v2, v3
	v_pk_mul_f32 v[2:3], v[2:3], v[0:1]
	v_fma_f32 v0, v0, v16, v1
	s_waitcnt lgkmcnt(2)
	v_fma_f32 v0, v6, v0, v7
	v_fma_f32 v0, v4, v0, v5
	s_waitcnt lgkmcnt(1)
	v_fma_f32 v1, v10, v0, v11
	v_mov_b32_e32 v0, v2
	v_mov_b32_e32 v16, v6
	v_mov_b32_e32 v17, v8
	v_pk_mul_f32 v[2:3], v[2:3], v[6:7]
	v_pk_fma_f32 v[0:1], v[0:1], v[16:17], v[8:9]
	v_pk_mul_f32 v[2:3], v[2:3], v[4:5]
	s_waitcnt lgkmcnt(0)
	v_mov_b32_e32 v11, v14
	v_mov_b32_e32 v3, v1
	v_pk_mul_f32 v[0:1], v[2:3], v[10:11]
	v_pk_fma_f32 v[2:3], v[2:3], v[10:11], v[14:15]
	v_pk_mul_f32 v[0:1], v[0:1], v[8:9]
	v_mov_b32_e32 v4, v14
	v_mov_b32_e32 v2, v0
	v_mov_b32_e32 v5, v12
	v_pk_mul_f32 v[0:1], v[0:1], v[14:15]
	v_pk_fma_f32 v[2:3], v[2:3], v[4:5], v[12:13]
	v_pk_mul_f32 v[0:1], v[0:1], v[12:13]
	s_nop 0
	v_mov_b32_e32 v1, v3
	v_lshl_add_u64 v[2:3], v[92:93], 3, s[30:31]
	global_store_dwordx2 v[2:3], v[0:1], off
